# removed the compiler-inserted full vmcnt(0) drain between the gemm8p prologue and its main loop in P2, P7 and one P3 copy (all older ops are already covered by the prologue's vmcnt(4))
# speedup vs baseline: 1.0047x; 1.0047x over previous
.LBB0_157:
	v_and_b32_e32 v3, 15, v2
	v_and_b32_e32 v16, 48, v2
	v_lshlrev_b32_e32 v2, 2, v2
	v_lshlrev_b32_e32 v3, 6, v3
	v_and_b32_e32 v2, 32, v2
	s_lshl_b32 s34, s34, 12
	v_lshl_add_u64 v[4:5], s[88:89], 0, v[0:1]
	v_mov_b32_e32 v135, v1
	v_or_b32_e32 v17, v3, v16
	v_bitop3_b32 v3, v3, v2, v16 bitop3:0x36
	s_lshl_b32 s33, s33, 13
	s_and_b32 s34, s34, 0x3000
	s_mov_b64 s[38:39], 0x80
	v_lshl_add_u64 v[6:7], s[88:89], 0, v[134:135]
	v_mov_b32_e32 v131, v1
	v_bitop3_b32 v136, v17, s33, v2 bitop3:0xde
	v_or_b32_e32 v137, s34, v3
	s_add_i32 m0, s5, 0x18000
	v_lshl_add_u64 v[2:3], v[4:5], 0, s[38:39]
	v_lshl_add_u64 v[8:9], s[0:1], 0, v[130:131]
	v_mov_b32_e32 v133, v1
	s_waitcnt vmcnt(4)
	s_barrier
	global_load_lds_dwordx4 v[2:3], off
	v_lshl_add_u64 v[2:3], v[6:7], 0, s[38:39]
	s_add_i32 m0, s5, 0x1a000
	s_add_i32 s33, s5, 0x8000
	v_lshl_add_u64 v[10:11], s[0:1], 0, v[132:133]
	global_load_lds_dwordx4 v[2:3], off
	v_lshl_add_u64 v[2:3], v[8:9], 0, s[38:39]
	s_mov_b32 m0, s33
	s_add_i32 s72, s5, 0xa000
	v_lshl_add_u64 v[12:13], s[64:65], 0, v[0:1]
	global_load_lds_dwordx4 v[2:3], off
	v_lshl_add_u64 v[2:3], v[10:11], 0, s[38:39]
	s_mov_b32 m0, s72
	v_lshl_add_u64 v[14:15], s[64:65], 0, v[134:135]
	global_load_lds_dwordx4 v[2:3], off
	s_add_i32 m0, s5, 0x1c000
	v_lshl_add_u64 v[2:3], v[12:13], 0, s[38:39]
	global_load_lds_dwordx4 v[2:3], off
	v_lshl_add_u64 v[2:3], v[14:15], 0, s[38:39]
	s_add_i32 m0, s5, 0x1e000
	v_mov_b32_e32 v5, 0
	global_load_lds_dwordx4 v[2:3], off
	s_waitcnt vmcnt(6)
	s_cmp_lt_i32 s20, 3
	v_mov_b32_e32 v4, v5
	v_mov_b32_e32 v3, v5
	v_mov_b32_e32 v2, v5
	v_mov_b32_e32 v9, v5
	v_mov_b32_e32 v8, v5
	v_mov_b32_e32 v7, v5
	v_mov_b32_e32 v6, v5
	v_mov_b32_e32 v13, v5
	v_mov_b32_e32 v12, v5
	v_mov_b32_e32 v11, v5
	v_mov_b32_e32 v10, v5
	v_mov_b32_e32 v17, v5
	v_mov_b32_e32 v16, v5
	v_mov_b32_e32 v15, v5
	v_mov_b32_e32 v14, v5
	v_mov_b32_e32 v21, v5
	v_mov_b32_e32 v20, v5
	v_mov_b32_e32 v19, v5
	v_mov_b32_e32 v18, v5
	v_mov_b32_e32 v25, v5
	v_mov_b32_e32 v24, v5
	v_mov_b32_e32 v23, v5
	v_mov_b32_e32 v22, v5
	v_mov_b32_e32 v29, v5
	v_mov_b32_e32 v28, v5
	v_mov_b32_e32 v27, v5
	v_mov_b32_e32 v26, v5
	v_mov_b32_e32 v33, v5
	v_mov_b32_e32 v32, v5
	v_mov_b32_e32 v31, v5
	v_mov_b32_e32 v30, v5
	v_mov_b32_e32 v37, v5
	v_mov_b32_e32 v36, v5
	v_mov_b32_e32 v35, v5
	v_mov_b32_e32 v34, v5
	v_mov_b32_e32 v41, v5
	v_mov_b32_e32 v40, v5
	v_mov_b32_e32 v39, v5
	v_mov_b32_e32 v38, v5
	v_mov_b32_e32 v45, v5
	v_mov_b32_e32 v44, v5
	v_mov_b32_e32 v43, v5
	v_mov_b32_e32 v42, v5
	v_mov_b32_e32 v49, v5
	v_mov_b32_e32 v48, v5
	v_mov_b32_e32 v47, v5
	v_mov_b32_e32 v46, v5
	v_mov_b32_e32 v53, v5
	v_mov_b32_e32 v52, v5
	v_mov_b32_e32 v51, v5
	v_mov_b32_e32 v50, v5
	v_mov_b32_e32 v57, v5
	v_mov_b32_e32 v56, v5
	v_mov_b32_e32 v55, v5
	v_mov_b32_e32 v54, v5
	v_mov_b32_e32 v61, v5
	v_mov_b32_e32 v60, v5
	v_mov_b32_e32 v59, v5
	v_mov_b32_e32 v58, v5
	s_nop 0
	v_mov_b32_e32 v65, v5
	v_mov_b32_e32 v64, v5
	v_mov_b32_e32 v63, v5
	v_mov_b32_e32 v62, v5
	v_mov_b32_e32 v69, v5
	v_mov_b32_e32 v68, v5
	v_mov_b32_e32 v67, v5
	v_mov_b32_e32 v66, v5
	v_mov_b32_e32 v73, v5
	v_mov_b32_e32 v72, v5
	v_mov_b32_e32 v71, v5
	v_mov_b32_e32 v70, v5
	v_mov_b32_e32 v77, v5
	v_mov_b32_e32 v76, v5
	v_mov_b32_e32 v75, v5
	v_mov_b32_e32 v74, v5
	v_mov_b32_e32 v81, v5
	v_mov_b32_e32 v80, v5
	v_mov_b32_e32 v79, v5
	v_mov_b32_e32 v78, v5
	v_mov_b32_e32 v85, v5
	v_mov_b32_e32 v84, v5
	v_mov_b32_e32 v83, v5
	v_mov_b32_e32 v82, v5
	v_mov_b32_e32 v89, v5
	v_mov_b32_e32 v88, v5
	v_mov_b32_e32 v87, v5
	v_mov_b32_e32 v86, v5
	v_mov_b32_e32 v93, v5
	v_mov_b32_e32 v92, v5
	v_mov_b32_e32 v91, v5
	v_mov_b32_e32 v90, v5
	v_mov_b32_e32 v97, v5
	v_mov_b32_e32 v96, v5
	v_mov_b32_e32 v95, v5
	v_mov_b32_e32 v94, v5
	v_mov_b32_e32 v129, v5
	v_mov_b32_e32 v128, v5
	v_mov_b32_e32 v127, v5
	v_mov_b32_e32 v126, v5
	v_mov_b32_e32 v125, v5
	v_mov_b32_e32 v124, v5
	v_mov_b32_e32 v123, v5
	v_mov_b32_e32 v122, v5
	v_mov_b32_e32 v121, v5
	v_mov_b32_e32 v120, v5
	v_mov_b32_e32 v119, v5
	v_mov_b32_e32 v118, v5
	v_mov_b32_e32 v117, v5
	v_mov_b32_e32 v116, v5
	v_mov_b32_e32 v115, v5
	v_mov_b32_e32 v114, v5
	v_mov_b32_e32 v113, v5
	v_mov_b32_e32 v112, v5
	v_mov_b32_e32 v111, v5
	v_mov_b32_e32 v110, v5
	v_mov_b32_e32 v109, v5
	v_mov_b32_e32 v108, v5
	v_mov_b32_e32 v107, v5
	v_mov_b32_e32 v106, v5
	v_mov_b32_e32 v105, v5
	v_mov_b32_e32 v104, v5
	v_mov_b32_e32 v103, v5
	v_mov_b32_e32 v102, v5
	v_mov_b32_e32 v101, v5
	v_mov_b32_e32 v100, v5
	v_mov_b32_e32 v99, v5
	v_mov_b32_e32 v98, v5
	s_barrier
	s_cbranch_scc1 .LBB0_160
	v_mov_b32_e32 v2, 0
	s_add_i32 s73, s20, -2
	s_mov_b32 s74, 0
	s_movk_i32 s38, 0xc0
	s_mov_b64 vcc, s[70:71]
	v_mov_b32_e32 v3, v2
	v_mov_b32_e32 v4, v2
	v_mov_b32_e32 v5, v2
	v_mov_b32_e32 v6, v2
	v_mov_b32_e32 v7, v2
	v_mov_b32_e32 v8, v2
	v_mov_b32_e32 v9, v2
	v_mov_b32_e32 v10, v2
	v_mov_b32_e32 v11, v2
	v_mov_b32_e32 v12, v2
	v_mov_b32_e32 v13, v2
	v_mov_b32_e32 v14, v2
	v_mov_b32_e32 v15, v2
	v_mov_b32_e32 v16, v2
	v_mov_b32_e32 v17, v2
	v_mov_b32_e32 v18, v2
	v_mov_b32_e32 v19, v2
	v_mov_b32_e32 v20, v2
	v_mov_b32_e32 v21, v2
	v_mov_b32_e32 v22, v2
	v_mov_b32_e32 v23, v2
	v_mov_b32_e32 v24, v2
	v_mov_b32_e32 v25, v2
	v_mov_b32_e32 v26, v2
	v_mov_b32_e32 v27, v2
	v_mov_b32_e32 v28, v2
	v_mov_b32_e32 v29, v2
	v_mov_b32_e32 v30, v2
	v_mov_b32_e32 v31, v2
	v_mov_b32_e32 v32, v2
	v_mov_b32_e32 v33, v2
	v_mov_b32_e32 v34, v2
	v_mov_b32_e32 v35, v2
	v_mov_b32_e32 v36, v2
	v_mov_b32_e32 v37, v2
	v_mov_b32_e32 v38, v2
	v_mov_b32_e32 v39, v2
	v_mov_b32_e32 v40, v2
	v_mov_b32_e32 v41, v2
	v_mov_b32_e32 v42, v2
	v_mov_b32_e32 v43, v2
	v_mov_b32_e32 v44, v2
	v_mov_b32_e32 v45, v2
	v_mov_b32_e32 v46, v2
	v_mov_b32_e32 v47, v2
	v_mov_b32_e32 v48, v2
	v_mov_b32_e32 v49, v2
	v_mov_b32_e32 v50, v2
	v_mov_b32_e32 v51, v2
	v_mov_b32_e32 v52, v2
	v_mov_b32_e32 v53, v2
	v_mov_b32_e32 v54, v2
	v_mov_b32_e32 v55, v2
	v_mov_b32_e32 v56, v2
	v_mov_b32_e32 v57, v2
	v_mov_b32_e32 v58, v2
	v_mov_b32_e32 v59, v2
	v_mov_b32_e32 v60, v2
	v_mov_b32_e32 v61, v2
	v_mov_b32_e32 v62, v2
	v_mov_b32_e32 v63, v2
	v_mov_b32_e32 v64, v2
	v_mov_b32_e32 v65, v2
	v_mov_b32_e32 v66, v2
	v_mov_b32_e32 v67, v2
	v_mov_b32_e32 v68, v2
	v_mov_b32_e32 v69, v2
	v_mov_b32_e32 v70, v2
	v_mov_b32_e32 v71, v2
	v_mov_b32_e32 v72, v2
	v_mov_b32_e32 v73, v2
	v_mov_b32_e32 v74, v2
	v_mov_b32_e32 v75, v2
	v_mov_b32_e32 v76, v2
	v_mov_b32_e32 v77, v2
	v_mov_b32_e32 v78, v2
	v_mov_b32_e32 v79, v2
	v_mov_b32_e32 v80, v2
	v_mov_b32_e32 v81, v2
	v_mov_b32_e32 v82, v2
	v_mov_b32_e32 v83, v2
	v_mov_b32_e32 v84, v2
	v_mov_b32_e32 v85, v2
	v_mov_b32_e32 v86, v2
	v_mov_b32_e32 v87, v2
	v_mov_b32_e32 v88, v2
	v_mov_b32_e32 v89, v2
	v_mov_b32_e32 v90, v2
	v_mov_b32_e32 v91, v2
	v_mov_b32_e32 v92, v2
	v_mov_b32_e32 v93, v2
	v_mov_b32_e32 v94, v2
	v_mov_b32_e32 v95, v2
	v_mov_b32_e32 v96, v2
	v_mov_b32_e32 v97, v2
	v_mov_b32_e32 v98, v2
	v_mov_b32_e32 v99, v2
	v_mov_b32_e32 v100, v2
	v_mov_b32_e32 v101, v2
	v_mov_b32_e32 v102, v2
	v_mov_b32_e32 v103, v2
	v_mov_b32_e32 v104, v2
	v_mov_b32_e32 v105, v2
	v_mov_b32_e32 v106, v2
	v_mov_b32_e32 v107, v2
	v_mov_b32_e32 v108, v2
	v_mov_b32_e32 v109, v2
	v_mov_b32_e32 v110, v2
	v_mov_b32_e32 v111, v2
	v_mov_b32_e32 v112, v2
	v_mov_b32_e32 v113, v2
	v_mov_b32_e32 v114, v2
	v_mov_b32_e32 v115, v2
	v_mov_b32_e32 v116, v2
	v_mov_b32_e32 v117, v2
	v_mov_b32_e32 v118, v2
	v_mov_b32_e32 v119, v2
	v_mov_b32_e32 v120, v2
	v_mov_b32_e32 v121, v2
	v_mov_b32_e32 v122, v2
	v_mov_b32_e32 v123, v2
	v_mov_b32_e32 v124, v2
	v_mov_b32_e32 v125, v2
	v_mov_b32_e32 v126, v2
	v_mov_b32_e32 v127, v2
	v_mov_b32_e32 v128, v2
	v_mov_b32_e32 v129, v2

.LBB0_244:
	v_and_b32_e32 v130, 15, v131
	v_lshl_add_u64 v[2:3], s[42:43], 0, v[0:1]
	v_mov_b32_e32 v137, v1
	v_and_b32_e32 v10, 48, v131
	v_lshlrev_b32_e32 v11, 6, v130
	v_lshlrev_b32_e32 v13, 2, v131
	s_mov_b64 s[48:49], 0x80
	v_lshl_add_u64 v[4:5], s[42:43], 0, v[136:137]
	v_mov_b32_e32 v133, v1
	v_or_b32_e32 v12, v11, v10
	v_and_b32_e32 v13, 32, v13
	s_lshl_b32 s18, s18, 12
	s_lshl_b32 s17, s17, 13
	s_add_i32 m0, s5, 0x18000
	v_lshl_add_u64 v[2:3], v[2:3], 0, s[48:49]
	v_lshl_add_u64 v[6:7], s[20:21], 0, v[132:133]
	v_mov_b32_e32 v135, v1
	v_bitop3_b32 v10, v11, v13, v10 bitop3:0x36
	s_and_b32 s18, s18, 0x3000
	v_bitop3_b32 v139, s17, v12, v13 bitop3:0xf6
	s_waitcnt vmcnt(4)
	s_barrier
	global_load_lds_dwordx4 v[2:3], off
	v_lshl_add_u64 v[2:3], v[4:5], 0, s[48:49]
	s_add_i32 m0, s5, 0x1a000
	s_add_i32 s17, s5, 0x8000
	v_lshl_add_u64 v[8:9], s[20:21], 0, v[134:135]
	v_or_b32_e32 v140, s18, v10
	global_load_lds_dwordx4 v[2:3], off
	v_lshl_add_u64 v[2:3], v[6:7], 0, s[48:49]
	s_mov_b32 m0, s17
	s_add_i32 s18, s5, 0xa000
	global_load_lds_dwordx4 v[2:3], off
	v_lshl_add_u64 v[2:3], v[8:9], 0, s[48:49]
	s_add_u32 s48, s42, 0x80080
	s_mov_b32 m0, s18
	s_addc_u32 s49, s43, 0
	global_load_lds_dwordx4 v[2:3], off
	s_add_i32 m0, s5, 0x1c000
	v_lshl_add_u64 v[2:3], s[48:49], 0, v[0:1]
	global_load_lds_dwordx4 v[2:3], off
	v_lshl_add_u64 v[2:3], s[48:49], 0, v[136:137]
	s_add_i32 m0, s5, 0x1e000
	v_mov_b32_e32 v5, 0
	global_load_lds_dwordx4 v[2:3], off
	s_waitcnt vmcnt(6)
	s_cmp_lt_i32 s40, 3
	v_mov_b32_e32 v4, v5
	v_mov_b32_e32 v3, v5
	v_mov_b32_e32 v2, v5
	v_mov_b32_e32 v9, v5
	v_mov_b32_e32 v8, v5
	v_mov_b32_e32 v7, v5
	v_mov_b32_e32 v6, v5
	v_mov_b32_e32 v13, v5
	v_mov_b32_e32 v12, v5
	v_mov_b32_e32 v11, v5
	v_mov_b32_e32 v10, v5
	v_mov_b32_e32 v17, v5
	v_mov_b32_e32 v16, v5
	v_mov_b32_e32 v15, v5
	v_mov_b32_e32 v14, v5
	v_mov_b32_e32 v21, v5
	v_mov_b32_e32 v20, v5
	v_mov_b32_e32 v19, v5
	v_mov_b32_e32 v18, v5
	v_mov_b32_e32 v25, v5
	v_mov_b32_e32 v24, v5
	v_mov_b32_e32 v23, v5
	v_mov_b32_e32 v22, v5
	v_mov_b32_e32 v29, v5
	v_mov_b32_e32 v28, v5
	v_mov_b32_e32 v27, v5
	v_mov_b32_e32 v26, v5
	v_mov_b32_e32 v33, v5
	v_mov_b32_e32 v32, v5
	v_mov_b32_e32 v31, v5
	v_mov_b32_e32 v30, v5
	v_mov_b32_e32 v37, v5
	v_mov_b32_e32 v36, v5
	v_mov_b32_e32 v35, v5
	v_mov_b32_e32 v34, v5
	v_mov_b32_e32 v41, v5
	v_mov_b32_e32 v40, v5
	v_mov_b32_e32 v39, v5
	v_mov_b32_e32 v38, v5
	v_mov_b32_e32 v45, v5
	v_mov_b32_e32 v44, v5
	v_mov_b32_e32 v43, v5
	v_mov_b32_e32 v42, v5
	v_mov_b32_e32 v49, v5
	v_mov_b32_e32 v48, v5
	v_mov_b32_e32 v47, v5
	v_mov_b32_e32 v46, v5
	v_mov_b32_e32 v53, v5
	v_mov_b32_e32 v52, v5
	v_mov_b32_e32 v51, v5
	v_mov_b32_e32 v50, v5
	v_mov_b32_e32 v57, v5
	v_mov_b32_e32 v56, v5
	v_mov_b32_e32 v55, v5
	v_mov_b32_e32 v54, v5
	v_mov_b32_e32 v61, v5
	v_mov_b32_e32 v60, v5
	v_mov_b32_e32 v59, v5
	v_mov_b32_e32 v58, v5
	s_nop 0
	v_mov_b32_e32 v65, v5
	v_mov_b32_e32 v64, v5
	v_mov_b32_e32 v63, v5
	v_mov_b32_e32 v62, v5
	v_mov_b32_e32 v69, v5
	v_mov_b32_e32 v68, v5
	v_mov_b32_e32 v67, v5
	v_mov_b32_e32 v66, v5
	v_mov_b32_e32 v73, v5
	v_mov_b32_e32 v72, v5
	v_mov_b32_e32 v71, v5
	v_mov_b32_e32 v70, v5
	v_mov_b32_e32 v77, v5
	v_mov_b32_e32 v76, v5
	v_mov_b32_e32 v75, v5
	v_mov_b32_e32 v74, v5
	v_mov_b32_e32 v81, v5
	v_mov_b32_e32 v80, v5
	v_mov_b32_e32 v79, v5
	v_mov_b32_e32 v78, v5
	v_mov_b32_e32 v85, v5
	v_mov_b32_e32 v84, v5
	v_mov_b32_e32 v83, v5
	v_mov_b32_e32 v82, v5
	v_mov_b32_e32 v89, v5
	v_mov_b32_e32 v88, v5
	v_mov_b32_e32 v87, v5
	v_mov_b32_e32 v86, v5
	v_mov_b32_e32 v93, v5
	v_mov_b32_e32 v92, v5
	v_mov_b32_e32 v91, v5
	v_mov_b32_e32 v90, v5
	v_mov_b32_e32 v97, v5
	v_mov_b32_e32 v96, v5
	v_mov_b32_e32 v95, v5
	v_mov_b32_e32 v94, v5
	v_mov_b32_e32 v101, v5
	v_mov_b32_e32 v100, v5
	v_mov_b32_e32 v99, v5
	v_mov_b32_e32 v98, v5
	v_mov_b32_e32 v105, v5
	v_mov_b32_e32 v104, v5
	v_mov_b32_e32 v103, v5
	v_mov_b32_e32 v102, v5
	v_mov_b32_e32 v109, v5
	v_mov_b32_e32 v108, v5
	v_mov_b32_e32 v107, v5
	v_mov_b32_e32 v106, v5
	v_mov_b32_e32 v113, v5
	v_mov_b32_e32 v112, v5
	v_mov_b32_e32 v111, v5
	v_mov_b32_e32 v110, v5
	v_mov_b32_e32 v117, v5
	v_mov_b32_e32 v116, v5
	v_mov_b32_e32 v115, v5
	v_mov_b32_e32 v114, v5
	v_mov_b32_e32 v121, v5
	v_mov_b32_e32 v120, v5
	v_mov_b32_e32 v119, v5
	v_mov_b32_e32 v118, v5
	v_mov_b32_e32 v125, v5
	v_mov_b32_e32 v124, v5
	v_mov_b32_e32 v123, v5
	v_mov_b32_e32 v122, v5
	v_mov_b32_e32 v129, v5
	v_mov_b32_e32 v128, v5
	v_mov_b32_e32 v127, v5
	v_mov_b32_e32 v126, v5
	s_barrier
	s_cbranch_scc1 .LBB0_247
	s_add_i32 s33, s40, -2
	s_add_u32 s34, s44, s34
	s_addc_u32 s37, s45, 0
	v_readlane_b32 s48, v252, 3
	v_readlane_b32 s49, v252, 4
	s_add_u32 s44, s48, s34
	v_mov_b32_e32 v2, 0
	s_addc_u32 s45, s49, s37
	s_mov_b32 s37, 0
	s_movk_i32 s48, 0xc0
	v_mov_b32_e32 v3, v2
	v_mov_b32_e32 v4, v2
	v_mov_b32_e32 v5, v2
	v_mov_b32_e32 v6, v2
	v_mov_b32_e32 v7, v2
	v_mov_b32_e32 v8, v2
	v_mov_b32_e32 v9, v2
	v_mov_b32_e32 v10, v2
	v_mov_b32_e32 v11, v2
	v_mov_b32_e32 v12, v2
	v_mov_b32_e32 v13, v2
	v_mov_b32_e32 v14, v2
	v_mov_b32_e32 v15, v2
	v_mov_b32_e32 v16, v2
	v_mov_b32_e32 v17, v2
	v_mov_b32_e32 v18, v2
	v_mov_b32_e32 v19, v2
	v_mov_b32_e32 v20, v2
	v_mov_b32_e32 v21, v2
	v_mov_b32_e32 v22, v2
	v_mov_b32_e32 v23, v2
	v_mov_b32_e32 v24, v2
	v_mov_b32_e32 v25, v2
	v_mov_b32_e32 v26, v2
	v_mov_b32_e32 v27, v2
	v_mov_b32_e32 v28, v2
	v_mov_b32_e32 v29, v2
	v_mov_b32_e32 v30, v2
	v_mov_b32_e32 v31, v2
	v_mov_b32_e32 v32, v2
	v_mov_b32_e32 v33, v2
	v_mov_b32_e32 v34, v2
	v_mov_b32_e32 v35, v2
	v_mov_b32_e32 v36, v2
	v_mov_b32_e32 v37, v2
	v_mov_b32_e32 v38, v2
	v_mov_b32_e32 v39, v2
	v_mov_b32_e32 v40, v2
	v_mov_b32_e32 v41, v2
	v_mov_b32_e32 v42, v2
	v_mov_b32_e32 v43, v2
	v_mov_b32_e32 v44, v2
	v_mov_b32_e32 v45, v2
	v_mov_b32_e32 v46, v2
	v_mov_b32_e32 v47, v2
	v_mov_b32_e32 v48, v2
	v_mov_b32_e32 v49, v2
	v_mov_b32_e32 v50, v2
	v_mov_b32_e32 v51, v2
	v_mov_b32_e32 v52, v2
	v_mov_b32_e32 v53, v2
	v_mov_b32_e32 v54, v2
	v_mov_b32_e32 v55, v2
	v_mov_b32_e32 v56, v2
	v_mov_b32_e32 v57, v2
	v_mov_b32_e32 v58, v2
	v_mov_b32_e32 v59, v2
	v_mov_b32_e32 v60, v2
	v_mov_b32_e32 v61, v2
	v_mov_b32_e32 v62, v2
	v_mov_b32_e32 v63, v2
	v_mov_b32_e32 v64, v2
	v_mov_b32_e32 v65, v2
	v_mov_b32_e32 v66, v2
	v_mov_b32_e32 v67, v2
	v_mov_b32_e32 v68, v2
	v_mov_b32_e32 v69, v2
	v_mov_b32_e32 v70, v2
	v_mov_b32_e32 v71, v2
	v_mov_b32_e32 v72, v2
	v_mov_b32_e32 v73, v2
	v_mov_b32_e32 v74, v2
	v_mov_b32_e32 v75, v2
	v_mov_b32_e32 v76, v2
	v_mov_b32_e32 v77, v2
	v_mov_b32_e32 v78, v2
	v_mov_b32_e32 v79, v2
	v_mov_b32_e32 v80, v2
	v_mov_b32_e32 v81, v2
	v_mov_b32_e32 v82, v2
	v_mov_b32_e32 v83, v2
	v_mov_b32_e32 v84, v2
	v_mov_b32_e32 v85, v2
	v_mov_b32_e32 v86, v2
	v_mov_b32_e32 v87, v2
	v_mov_b32_e32 v88, v2
	v_mov_b32_e32 v89, v2
	v_mov_b32_e32 v90, v2
	v_mov_b32_e32 v91, v2
	v_mov_b32_e32 v92, v2
	v_mov_b32_e32 v93, v2
	v_mov_b32_e32 v94, v2
	v_mov_b32_e32 v95, v2
	v_mov_b32_e32 v96, v2
	v_mov_b32_e32 v97, v2
	v_mov_b32_e32 v98, v2
	v_mov_b32_e32 v99, v2
	v_mov_b32_e32 v100, v2
	v_mov_b32_e32 v101, v2
	v_mov_b32_e32 v102, v2
	v_mov_b32_e32 v103, v2
	v_mov_b32_e32 v104, v2
	v_mov_b32_e32 v105, v2
	v_mov_b32_e32 v106, v2
	v_mov_b32_e32 v107, v2
	v_mov_b32_e32 v108, v2
	v_mov_b32_e32 v109, v2
	v_mov_b32_e32 v110, v2
	v_mov_b32_e32 v111, v2
	v_mov_b32_e32 v112, v2
	v_mov_b32_e32 v113, v2
	v_mov_b32_e32 v114, v2
	v_mov_b32_e32 v115, v2
	v_mov_b32_e32 v116, v2
	v_mov_b32_e32 v117, v2
	v_mov_b32_e32 v118, v2
	v_mov_b32_e32 v119, v2
	v_mov_b32_e32 v120, v2
	v_mov_b32_e32 v121, v2
	v_mov_b32_e32 v122, v2
	v_mov_b32_e32 v123, v2
	v_mov_b32_e32 v124, v2
	v_mov_b32_e32 v125, v2
	v_mov_b32_e32 v126, v2
	v_mov_b32_e32 v127, v2
	v_mov_b32_e32 v128, v2
	v_mov_b32_e32 v129, v2
	s_mov_b64 s[70:71], 0x2bb680
	s_mov_b64 s[72:73], 0x23b700
	s_mov_b64 s[74:75], 0x2bb700
	s_mov_b64 s[76:77], 0x23b780
	v_readlane_b32 s50, v252, 5
	v_readlane_b32 s51, v252, 6

.LBB0_301:
	s_lshl_b32 s42, s42, 12
	s_and_b32 s42, s42, 0x3000
	v_lshl_add_u64 v[2:3], s[40:41], 0, v[0:1]
	v_mov_b32_e32 v153, v1
	v_or_b32_e32 v147, s42, v163
	s_mov_b64 s[42:43], 0x80
	v_lshl_add_u64 v[4:5], s[40:41], 0, v[152:153]
	v_mov_b32_e32 v151, v1
	s_add_i32 m0, s7, 0x18000
	v_lshl_add_u64 v[2:3], v[2:3], 0, s[42:43]
	v_lshl_add_u64 v[6:7], s[0:1], 0, v[150:151]
	v_mov_b32_e32 v149, v1
	s_waitcnt vmcnt(4)
	s_barrier
	global_load_lds_dwordx4 v[2:3], off
	v_lshl_add_u64 v[2:3], v[4:5], 0, s[42:43]
	s_add_i32 m0, s7, 0x1a000
	s_add_i32 s62, s7, 0x8000
	v_lshl_add_u64 v[8:9], s[0:1], 0, v[148:149]
	s_bfe_u32 s11, s52, 0x30008
	global_load_lds_dwordx4 v[2:3], off
	v_lshl_add_u64 v[2:3], v[6:7], 0, s[42:43]
	s_mov_b32 m0, s62
	s_add_i32 s63, s7, 0xa000
	global_load_lds_dwordx4 v[2:3], off
	v_lshl_add_u64 v[2:3], v[8:9], 0, s[42:43]
	s_add_u32 s42, s40, 0x40080
	s_mov_b32 m0, s63
	s_addc_u32 s43, s41, 0
	global_load_lds_dwordx4 v[2:3], off
	s_add_i32 m0, s7, 0x1c000
	v_lshl_add_u64 v[2:3], s[42:43], 0, v[0:1]
	global_load_lds_dwordx4 v[2:3], off
	v_lshl_add_u64 v[2:3], s[42:43], 0, v[152:153]
	s_add_i32 m0, s7, 0x1e000
	v_mov_b32_e32 v129, 0
	global_load_lds_dwordx4 v[2:3], off
	s_waitcnt vmcnt(6)
	v_lshl_or_b32 v145, s34, 13, v163
	s_cmp_lt_i32 s20, 3
	v_mov_b32_e32 v128, v129
	v_mov_b32_e32 v127, v129
	v_mov_b32_e32 v126, v129
	v_mov_b32_e32 v125, v129
	v_mov_b32_e32 v124, v129
	v_mov_b32_e32 v123, v129
	v_mov_b32_e32 v122, v129
	v_mov_b32_e32 v121, v129
	v_mov_b32_e32 v120, v129
	v_mov_b32_e32 v119, v129
	v_mov_b32_e32 v118, v129
	v_mov_b32_e32 v117, v129
	v_mov_b32_e32 v116, v129
	v_mov_b32_e32 v115, v129
	v_mov_b32_e32 v114, v129
	v_mov_b32_e32 v113, v129
	v_mov_b32_e32 v112, v129
	v_mov_b32_e32 v111, v129
	v_mov_b32_e32 v110, v129
	v_mov_b32_e32 v109, v129
	v_mov_b32_e32 v108, v129
	v_mov_b32_e32 v107, v129
	v_mov_b32_e32 v106, v129
	v_mov_b32_e32 v105, v129
	v_mov_b32_e32 v104, v129
	v_mov_b32_e32 v103, v129
	v_mov_b32_e32 v102, v129
	v_mov_b32_e32 v101, v129
	v_mov_b32_e32 v100, v129
	v_mov_b32_e32 v99, v129
	v_mov_b32_e32 v98, v129
	v_mov_b32_e32 v97, v129
	v_mov_b32_e32 v96, v129
	s_nop 0
	v_mov_b32_e32 v95, v129
	v_mov_b32_e32 v94, v129
	v_mov_b32_e32 v93, v129
	v_mov_b32_e32 v92, v129
	v_mov_b32_e32 v91, v129
	v_mov_b32_e32 v90, v129
	v_mov_b32_e32 v89, v129
	v_mov_b32_e32 v88, v129
	v_mov_b32_e32 v87, v129
	v_mov_b32_e32 v86, v129
	v_mov_b32_e32 v85, v129
	v_mov_b32_e32 v84, v129
	v_mov_b32_e32 v83, v129
	v_mov_b32_e32 v82, v129
	v_mov_b32_e32 v81, v129
	v_mov_b32_e32 v80, v129
	v_mov_b32_e32 v79, v129
	v_mov_b32_e32 v78, v129
	v_mov_b32_e32 v77, v129
	v_mov_b32_e32 v76, v129
	v_mov_b32_e32 v75, v129
	v_mov_b32_e32 v74, v129
	v_mov_b32_e32 v73, v129
	v_mov_b32_e32 v72, v129
	v_mov_b32_e32 v71, v129
	v_mov_b32_e32 v70, v129
	v_mov_b32_e32 v69, v129
	v_mov_b32_e32 v68, v129
	v_mov_b32_e32 v67, v129
	v_mov_b32_e32 v66, v129
	v_mov_b32_e32 v65, v129
	v_mov_b32_e32 v64, v129
	v_mov_b32_e32 v63, v129
	v_mov_b32_e32 v62, v129
	v_mov_b32_e32 v61, v129
	v_mov_b32_e32 v60, v129
	v_mov_b32_e32 v59, v129
	v_mov_b32_e32 v58, v129
	v_mov_b32_e32 v57, v129
	v_mov_b32_e32 v56, v129
	v_mov_b32_e32 v55, v129
	v_mov_b32_e32 v54, v129
	v_mov_b32_e32 v53, v129
	v_mov_b32_e32 v52, v129
	v_mov_b32_e32 v51, v129
	v_mov_b32_e32 v50, v129
	v_mov_b32_e32 v49, v129
	v_mov_b32_e32 v48, v129
	v_mov_b32_e32 v47, v129
	v_mov_b32_e32 v46, v129
	v_mov_b32_e32 v45, v129
	v_mov_b32_e32 v44, v129
	v_mov_b32_e32 v43, v129
	v_mov_b32_e32 v42, v129
	v_mov_b32_e32 v41, v129
	v_mov_b32_e32 v40, v129
	v_mov_b32_e32 v39, v129
	v_mov_b32_e32 v38, v129
	v_mov_b32_e32 v33, v129
	v_mov_b32_e32 v32, v129
	v_mov_b32_e32 v31, v129
	v_mov_b32_e32 v30, v129
	v_mov_b32_e32 v37, v129
	v_mov_b32_e32 v36, v129
	v_mov_b32_e32 v35, v129
	v_mov_b32_e32 v34, v129
	v_mov_b32_e32 v29, v129
	v_mov_b32_e32 v28, v129
	v_mov_b32_e32 v27, v129
	v_mov_b32_e32 v26, v129
	v_mov_b32_e32 v25, v129
	v_mov_b32_e32 v24, v129
	v_mov_b32_e32 v23, v129
	v_mov_b32_e32 v22, v129
	v_mov_b32_e32 v21, v129
	v_mov_b32_e32 v20, v129
	v_mov_b32_e32 v19, v129
	v_mov_b32_e32 v18, v129
	v_mov_b32_e32 v17, v129
	v_mov_b32_e32 v16, v129
	v_mov_b32_e32 v15, v129
	v_mov_b32_e32 v14, v129
	v_mov_b32_e32 v13, v129
	v_mov_b32_e32 v12, v129
	v_mov_b32_e32 v11, v129
	v_mov_b32_e32 v10, v129
	v_mov_b32_e32 v9, v129
	v_mov_b32_e32 v8, v129
	v_mov_b32_e32 v7, v129
	v_mov_b32_e32 v6, v129
	v_mov_b32_e32 v5, v129
	v_mov_b32_e32 v4, v129
	v_mov_b32_e32 v3, v129
	v_mov_b32_e32 v2, v129
	s_mov_b64 s[80:81], 0x100
	s_mov_b64 s[82:83], 0x17db680
	s_mov_b64 s[84:85], 0x175b700
	s_mov_b64 s[86:87], 0x17db700
	s_mov_b64 s[88:89], 0x175b780
	s_barrier
	s_cbranch_scc1 .LBB0_305
	s_lshl_b64 s[42:43], s[38:39], 10
	s_add_i32 s64, s20, -2
	s_lshl_b32 s34, s11, 20
	s_lshl_b64 s[42:43], s[42:43], 1
	s_add_u32 s65, s17, s42
	s_addc_u32 s66, s18, s43
	v_readlane_b32 s68, v252, 3
	v_readlane_b32 s69, v252, 4
	s_add_u32 s42, s68, s34
	s_addc_u32 s43, s69, 0
	v_mov_b32_e32 v2, 0
	v_mov_b64_e32 v[244:245], v[156:157]
	v_lshl_add_u64 v[154:155], s[42:43], 0, v[150:151]
	v_lshl_add_u64 v[156:157], s[42:43], 0, v[148:149]
	s_mov_b32 s67, 0
	s_movk_i32 s42, 0xc0
	v_mov_b32_e32 v3, v2
	v_mov_b32_e32 v4, v2
	v_mov_b32_e32 v5, v2
	v_mov_b32_e32 v6, v2
	v_mov_b32_e32 v7, v2
	v_mov_b32_e32 v8, v2
	v_mov_b32_e32 v9, v2
	v_mov_b32_e32 v10, v2
	v_mov_b32_e32 v11, v2
	v_mov_b32_e32 v12, v2
	v_mov_b32_e32 v13, v2
	v_mov_b32_e32 v14, v2
	v_mov_b32_e32 v15, v2
	v_mov_b32_e32 v16, v2
	v_mov_b32_e32 v17, v2
	v_mov_b32_e32 v18, v2
	v_mov_b32_e32 v19, v2
	v_mov_b32_e32 v20, v2
	v_mov_b32_e32 v21, v2
	v_mov_b32_e32 v22, v2
	v_mov_b32_e32 v23, v2
	v_mov_b32_e32 v24, v2
	v_mov_b32_e32 v25, v2
	v_mov_b32_e32 v26, v2
	v_mov_b32_e32 v27, v2
	v_mov_b32_e32 v28, v2
	v_mov_b32_e32 v29, v2
	v_mov_b32_e32 v34, v2
	v_mov_b32_e32 v35, v2
	v_mov_b32_e32 v36, v2
	v_mov_b32_e32 v37, v2
	v_mov_b32_e32 v30, v2
	v_mov_b32_e32 v31, v2
	v_mov_b32_e32 v32, v2
	v_mov_b32_e32 v33, v2
	v_mov_b32_e32 v38, v2
	v_mov_b32_e32 v39, v2
	v_mov_b32_e32 v40, v2
	v_mov_b32_e32 v41, v2
	v_mov_b32_e32 v42, v2
	v_mov_b32_e32 v43, v2
	v_mov_b32_e32 v44, v2
	v_mov_b32_e32 v45, v2
	v_mov_b32_e32 v46, v2
	v_mov_b32_e32 v47, v2
	v_mov_b32_e32 v48, v2
	v_mov_b32_e32 v49, v2
	v_mov_b32_e32 v50, v2
	v_mov_b32_e32 v51, v2
	v_mov_b32_e32 v52, v2
	v_mov_b32_e32 v53, v2
	v_mov_b32_e32 v54, v2
	v_mov_b32_e32 v55, v2
	v_mov_b32_e32 v56, v2
	v_mov_b32_e32 v57, v2
	v_mov_b32_e32 v58, v2
	v_mov_b32_e32 v59, v2
	v_mov_b32_e32 v60, v2
	v_mov_b32_e32 v61, v2
	v_mov_b32_e32 v62, v2
	v_mov_b32_e32 v63, v2
	v_mov_b32_e32 v64, v2
	v_mov_b32_e32 v65, v2
	v_mov_b32_e32 v66, v2
	v_mov_b32_e32 v67, v2
	v_mov_b32_e32 v68, v2
	v_mov_b32_e32 v69, v2
	v_mov_b32_e32 v70, v2
	v_mov_b32_e32 v71, v2
	v_mov_b32_e32 v72, v2
	v_mov_b32_e32 v73, v2
	v_mov_b32_e32 v74, v2
	v_mov_b32_e32 v75, v2
	v_mov_b32_e32 v76, v2
	v_mov_b32_e32 v77, v2
	v_mov_b32_e32 v78, v2
	v_mov_b32_e32 v79, v2
	v_mov_b32_e32 v80, v2
	v_mov_b32_e32 v81, v2
	v_mov_b32_e32 v82, v2
	v_mov_b32_e32 v83, v2
	v_mov_b32_e32 v84, v2
	v_mov_b32_e32 v85, v2
	v_mov_b32_e32 v86, v2
	v_mov_b32_e32 v87, v2
	v_mov_b32_e32 v88, v2
	v_mov_b32_e32 v89, v2
	v_mov_b32_e32 v90, v2
	v_mov_b32_e32 v91, v2
	v_mov_b32_e32 v92, v2
	v_mov_b32_e32 v93, v2
	v_mov_b32_e32 v94, v2
	v_mov_b32_e32 v95, v2
	v_mov_b32_e32 v96, v2
	v_mov_b32_e32 v97, v2
	v_mov_b32_e32 v98, v2
	v_mov_b32_e32 v99, v2
	v_mov_b32_e32 v100, v2
	v_mov_b32_e32 v101, v2
	v_mov_b32_e32 v102, v2
	v_mov_b32_e32 v103, v2
	v_mov_b32_e32 v104, v2
	v_mov_b32_e32 v105, v2
	v_mov_b32_e32 v106, v2
	v_mov_b32_e32 v107, v2
	v_mov_b32_e32 v108, v2
	v_mov_b32_e32 v109, v2
	v_mov_b32_e32 v110, v2
	v_mov_b32_e32 v111, v2
	v_mov_b32_e32 v112, v2
	v_mov_b32_e32 v113, v2
	v_mov_b32_e32 v114, v2
	v_mov_b32_e32 v115, v2
	v_mov_b32_e32 v116, v2
	v_mov_b32_e32 v117, v2
	v_mov_b32_e32 v118, v2
	v_mov_b32_e32 v119, v2
	v_mov_b32_e32 v120, v2
	v_mov_b32_e32 v121, v2
	v_mov_b32_e32 v122, v2
	v_mov_b32_e32 v123, v2
	v_mov_b32_e32 v124, v2
	v_mov_b32_e32 v125, v2
	v_mov_b32_e32 v126, v2
	v_mov_b32_e32 v127, v2
	v_mov_b32_e32 v128, v2
	v_mov_b32_e32 v129, v2
	v_readlane_b32 s70, v252, 5
	v_readlane_b32 s71, v252, 6
